# strategy: one static priority raise per GEMM job for waves 0-3, per-cluster s_setprio flips deleted
# speedup vs baseline: 1.0191x; 1.0059x over previous
.LBB0_361:
	s_add_u32 s34, s14, 0
	s_addc_u32 s21, s15, s21
	s_add_u32 s34, s34, s19
	s_addc_u32 s35, s21, 0
	s_add_u32 s19, s14, 0
	s_addc_u32 s21, s15, s25
	s_add_u32 s36, s19, s20
	s_addc_u32 s37, s21, 0
	s_add_i32 m0, s73, 0x18000
	v_lshl_add_u64 v[4:5], v[4:5], 0, s[86:87]
	s_waitcnt vmcnt(4)
	s_barrier
	global_load_lds_dwordx4 v[4:5], off
	v_lshl_add_u64 v[4:5], v[6:7], 0, s[86:87]
	s_add_i32 m0, s73, 0x1a000
	s_add_i32 s77, s73, 0x8000
	global_load_lds_dwordx4 v[4:5], off
	v_lshl_add_u64 v[4:5], v[8:9], 0, s[86:87]
	s_mov_b32 m0, s77
	s_add_i32 s64, s73, 0xa000
	global_load_lds_dwordx4 v[4:5], off
	v_lshl_add_u64 v[4:5], v[10:11], 0, s[86:87]
	s_mov_b32 m0, s64
	s_lshr_b32 s19, s51, 26
	global_load_lds_dwordx4 v[4:5], off
	s_add_i32 m0, s73, 0x1c000
	v_lshl_add_u64 v[4:5], v[12:13], 0, s[86:87]
	global_load_lds_dwordx4 v[4:5], off
	v_lshl_add_u64 v[4:5], v[14:15], 0, s[86:87]
	s_add_i32 m0, s73, 0x1e000
	s_add_i32 s19, s50, s19
	global_load_lds_dwordx4 v[4:5], off
	v_lshlrev_b32_e32 v16, 2, v228
	s_ashr_i32 s67, s19, 6
	v_lshl_or_b32 v1, v228, 6, v230
	s_lshl_b32 s19, s38, 13
	v_and_b32_e32 v16, 32, v16
	v_bitop3_b32 v1, v1, s19, v16 bitop3:0xde
	s_lshl_b32 s19, s39, 5
	s_and_b32 s46, s19, 0x60
	s_cmp_gt_i32 s50, 63
	v_lshl_or_b32 v199, s38, 6, v228
	s_cselect_b64 s[38:39], -1, 0
	s_ashr_i32 s20, s18, 31
	s_lshr_b32 s20, s20, 29
	s_add_i32 s20, s18, s20
	s_ashr_i32 s44, s20, 3
	s_and_b32 s20, s20, -8
	s_ashr_i32 s19, s16, 31
	s_ashr_i32 s53, s95, 31
	s_ashr_i32 s25, s24, 31
	s_sub_i32 s45, s18, s20
	s_add_i32 s65, s44, 1
	s_lshl_b32 s74, s9, 3
	s_add_i32 s75, s67, -2
	s_ashr_i32 s9, s17, 31
	s_add_u32 s80, s17, s16
	v_sub_co_u32_e64 v4, s[16:17], s1, 1
	s_addc_u32 s82, s9, s19
	s_xor_b64 s[40:41], s[16:17], -1
	s_cmp_gt_i32 s1, 3
	s_cselect_b64 s[42:43], -1, 0
	s_cmp_lg_u32 s1, 4
	s_cselect_b64 s[48:49], -1, 0
	s_ashr_i32 s9, s8, 31
	s_lshl_b64 s[8:9], s[8:9], 2
	s_add_u32 s84, s14, s8
	s_addc_u32 s16, s15, s9
	s_add_u32 s17, s14, 0x198100
	s_addc_u32 s18, s15, 0
	s_abs_i32 s20, s74
	v_lshlrev_b32_e32 v204, 10, v4
	v_cmp_ne_u32_e64 s[8:9], 0, v4
	v_cvt_f32_u32_e32 v4, s20
	s_sub_i32 s1, 0, s20
	s_waitcnt vmcnt(6)
	s_mov_b32 s66, 0
	v_rcp_iflag_f32_e32 v4, v4
	v_lshl_or_b32 v238, s46, 7, v231
	v_or_b32_e32 v239, s46, v229
	v_ashrrev_i32_e32 v205, 31, v204
	v_mul_f32_e32 v4, 0x4f7ffffe, v4
	v_cvt_u32_f32_e32 v4, v4
	s_ashr_i32 s19, s74, 31
	v_add_u32_e32 v240, 0, v1
	s_lshl_b32 s46, s46, 2
	v_readfirstlane_b32 s14, v4
	s_mul_i32 s1, s1, s14
	s_mul_hi_u32 s1, s14, s1
	v_lshlrev_b32_e32 v4, 1, v226
	s_add_i32 s21, s14, s1
	v_mad_u64_u32 v[4:5], s[14:15], v4, s50, v[196:197]
	v_mov_b32_e32 v5, v2
	v_lshl_add_u64 v[206:207], s[28:29], 0, v[4:5]
	v_lshlrev_b32_e32 v4, 1, v227
	v_mad_u64_u32 v[4:5], s[14:15], v4, s50, v[196:197]
	v_mov_b32_e32 v5, v2
	v_lshl_add_u64 v[208:209], s[28:29], 0, v[4:5]
	s_barrier
	v_readfirstlane_b32 s32, v197
	s_nop 3
	s_lshr_b32 s32, s32, 8
	s_cmp_eq_u32 s32, 0
	s_cbranch_scc0 .Lprio_skip
	s_setprio 1
.Lprio_skip:
	s_mov_b32 s32, 0
	s_branch .LBB0_363

.Lk_go:
	s_add_u32 s4, s4, 0x80
	s_addc_u32 s5, s5, 0
	s_add_u32 s1, s10, 0x100
	s_addc_u32 vcc_lo, s11, 0
	s_mov_b32 s10, 0
	s_cmp_eq_u32 s32, 1
	s_cbranch_scc1 .Lk_goB
	s_add_i32 vcc_hi, s10, 2
	s_add_u32 s56, s4, 0x80
	s_addc_u32 s11, s5, 0
	s_add_i32 s98, 0, 0x10000
	v_add_u32_e32 v1, s98, v238
	ds_read_b128 v[132:135], v1
	ds_read_b128 v[136:139], v1 offset:1024
	ds_read_b128 v[140:143], v1 offset:2048
	ds_read_b128 v[144:147], v1 offset:3072
	s_cmp_eq_u32 s75, s10
	s_cselect_b32 s10, s50, s56
	s_cselect_b32 s11, s51, s11
	s_cselect_b32 s57, s97, vcc_lo
	s_cselect_b32 s56, s96, s1
	v_lshl_add_u64 v[180:181], s[4:5], 0, v[206:207]
	s_add_i32 m0, s73, 0xc000
	ds_read_b128 v[148:151], v240
	ds_read_b128 v[152:155], v240 offset:1024
	ds_read_b128 v[156:159], v240 offset:2048
	ds_read_b128 v[160:163], v240 offset:3072
	ds_read_b128 v[164:167], v240 offset:4096
	ds_read_b128 v[168:171], v240 offset:5120
	ds_read_b128 v[172:175], v240 offset:6144
	ds_read_b128 v[176:179], v240 offset:7168
	global_load_lds_dwordx4 v[180:181], off
	v_lshl_add_u64 v[180:181], s[4:5], 0, v[208:209]
	s_add_i32 m0, s73, 0xe000
	s_nop 0
	global_load_lds_dwordx4 v[180:181], off
	s_waitcnt lgkmcnt(8)
	s_waitcnt vmcnt(10)
	s_barrier
	s_waitcnt lgkmcnt(0)
	s_waitcnt lgkmcnt(0)
	v_mfma_f32_16x16x32_f16 v[124:127], v[132:135], v[148:151], 0
	v_mfma_f32_16x16x32_f16 v[128:131], v[140:143], v[148:151], 0
	v_mfma_f32_16x16x32_f16 v[108:111], v[132:135], v[156:159], 0
	v_mfma_f32_16x16x32_f16 v[112:115], v[140:143], v[156:159], 0
	v_mfma_f32_16x16x32_f16 v[92:95], v[132:135], v[164:167], 0
	v_mfma_f32_16x16x32_f16 v[96:99], v[140:143], v[164:167], 0
	v_mfma_f32_16x16x32_f16 v[76:79], v[132:135], v[172:175], 0
	v_mfma_f32_16x16x32_f16 v[80:83], v[140:143], v[172:175], 0
	v_mfma_f32_16x16x32_f16 v[124:127], v[136:139], v[152:155], v[124:127]
	v_mfma_f32_16x16x32_f16 v[128:131], v[144:147], v[152:155], v[128:131]
	v_mfma_f32_16x16x32_f16 v[108:111], v[136:139], v[160:163], v[108:111]
	v_mfma_f32_16x16x32_f16 v[112:115], v[144:147], v[160:163], v[112:115]
	v_mfma_f32_16x16x32_f16 v[92:95], v[136:139], v[168:171], v[92:95]
	v_mfma_f32_16x16x32_f16 v[96:99], v[144:147], v[168:171], v[96:99]
	v_mfma_f32_16x16x32_f16 v[76:79], v[136:139], v[176:179], v[76:79]
	v_mfma_f32_16x16x32_f16 v[80:83], v[144:147], v[176:179], v[80:83]
	s_barrier
	s_add_i32 s98, s98, s72
	v_add_u32_e32 v1, s58, v238
	v_lshl_add_u64 v[210:211], s[56:57], 0, v[200:201]
	s_mov_b32 m0, s98
	ds_read_b128 v[180:183], v1
	ds_read_b128 v[184:187], v1 offset:1024
	ds_read_b128 v[188:191], v1 offset:2048
	ds_read_b128 v[192:195], v1 offset:3072
	global_load_lds_dwordx4 v[210:211], off
	v_lshl_add_u64 v[212:213], s[56:57], 0, v[202:203]
	s_add_i32 m0, s98, 0x2000
	s_nop 0
	global_load_lds_dwordx4 v[212:213], off
	s_waitcnt vmcnt(10)
	s_barrier
	s_waitcnt lgkmcnt(0)
	s_waitcnt lgkmcnt(0)
	v_mfma_f32_16x16x32_f16 v[116:119], v[180:183], v[148:151], 0
	v_mfma_f32_16x16x32_f16 v[120:123], v[188:191], v[148:151], 0
	v_mfma_f32_16x16x32_f16 v[100:103], v[180:183], v[156:159], 0
	v_mfma_f32_16x16x32_f16 v[104:107], v[188:191], v[156:159], 0
	v_mfma_f32_16x16x32_f16 v[84:87], v[180:183], v[164:167], 0
	v_mfma_f32_16x16x32_f16 v[88:91], v[188:191], v[164:167], 0
	v_mfma_f32_16x16x32_f16 v[68:71], v[180:183], v[172:175], 0
	v_mfma_f32_16x16x32_f16 v[72:75], v[188:191], v[172:175], 0
	v_mfma_f32_16x16x32_f16 v[116:119], v[184:187], v[152:155], v[116:119]
	v_mfma_f32_16x16x32_f16 v[120:123], v[192:195], v[152:155], v[120:123]
	v_mfma_f32_16x16x32_f16 v[100:103], v[184:187], v[160:163], v[100:103]
	v_mfma_f32_16x16x32_f16 v[104:107], v[192:195], v[160:163], v[104:107]
	v_mfma_f32_16x16x32_f16 v[84:87], v[184:187], v[168:171], v[84:87]
	v_mfma_f32_16x16x32_f16 v[88:91], v[192:195], v[168:171], v[88:91]
	v_mfma_f32_16x16x32_f16 v[68:71], v[184:187], v[176:179], v[68:71]
	v_mfma_f32_16x16x32_f16 v[72:75], v[192:195], v[176:179], v[72:75]
	s_mov_b32 m0, s73
	v_lshl_add_u64 v[214:215], s[10:11], 0, v[200:201]
	s_barrier
	ds_read_b128 v[148:151], v240 offset:16384
	ds_read_b128 v[152:155], v240 offset:17408
	ds_read_b128 v[156:159], v240 offset:18432
	ds_read_b128 v[160:163], v240 offset:19456
	ds_read_b128 v[164:167], v240 offset:20480
	ds_read_b128 v[168:171], v240 offset:21504
	ds_read_b128 v[172:175], v240 offset:22528
	ds_read_b128 v[176:179], v240 offset:23552
	global_load_lds_dwordx4 v[214:215], off
	v_lshl_add_u64 v[216:217], s[10:11], 0, v[202:203]
	s_mov_b32 m0, s78
	s_nop 0
	global_load_lds_dwordx4 v[216:217], off
	s_barrier
	s_waitcnt lgkmcnt(0)
	s_waitcnt lgkmcnt(0)
	v_mfma_f32_16x16x32_f16 v[60:63], v[132:135], v[148:151], 0
	v_mfma_f32_16x16x32_f16 v[64:67], v[140:143], v[148:151], 0
	v_mfma_f32_16x16x32_f16 v[44:47], v[132:135], v[156:159], 0
	v_mfma_f32_16x16x32_f16 v[48:51], v[140:143], v[156:159], 0
	v_mfma_f32_16x16x32_f16 v[28:31], v[132:135], v[164:167], 0
	v_mfma_f32_16x16x32_f16 v[32:35], v[140:143], v[164:167], 0
	v_mfma_f32_16x16x32_f16 v[12:15], v[132:135], v[172:175], 0
	v_mfma_f32_16x16x32_f16 v[16:19], v[140:143], v[172:175], 0
	v_mfma_f32_16x16x32_f16 v[60:63], v[136:139], v[152:155], v[60:63]
	v_mfma_f32_16x16x32_f16 v[64:67], v[144:147], v[152:155], v[64:67]
	v_mfma_f32_16x16x32_f16 v[44:47], v[136:139], v[160:163], v[44:47]
	v_mfma_f32_16x16x32_f16 v[48:51], v[144:147], v[160:163], v[48:51]
	v_mfma_f32_16x16x32_f16 v[28:31], v[136:139], v[168:171], v[28:31]
	v_mfma_f32_16x16x32_f16 v[32:35], v[144:147], v[168:171], v[32:35]
	v_mfma_f32_16x16x32_f16 v[12:15], v[136:139], v[176:179], v[12:15]
	v_mfma_f32_16x16x32_f16 v[16:19], v[144:147], v[176:179], v[16:19]
	s_barrier
	s_add_u32 s56, s56, s28
	s_addc_u32 s57, s57, s29
	s_add_i32 s98, s58, s72
	v_lshl_add_u64 v[218:219], s[56:57], 0, v[200:201]
	s_mov_b32 m0, s98
	v_lshl_add_u64 v[220:221], s[56:57], 0, v[202:203]
	global_load_lds_dwordx4 v[218:219], off
	s_add_i32 m0, s98, 0x2000
	s_nop 0
	global_load_lds_dwordx4 v[220:221], off
	s_waitcnt vmcnt(10)
	s_barrier
	v_mfma_f32_16x16x32_f16 v[52:55], v[180:183], v[148:151], 0
	v_mfma_f32_16x16x32_f16 v[56:59], v[188:191], v[148:151], 0
	v_mfma_f32_16x16x32_f16 v[36:39], v[180:183], v[156:159], 0
	v_mfma_f32_16x16x32_f16 v[40:43], v[188:191], v[156:159], 0
	v_mfma_f32_16x16x32_f16 v[20:23], v[180:183], v[164:167], 0
	v_mfma_f32_16x16x32_f16 v[24:27], v[188:191], v[164:167], 0
	v_mfma_f32_16x16x32_f16 v[8:11], v[180:183], v[172:175], 0
	v_mfma_f32_16x16x32_f16 v[4:7], v[188:191], v[172:175], 0
	v_mfma_f32_16x16x32_f16 v[52:55], v[184:187], v[152:155], v[52:55]
	v_mfma_f32_16x16x32_f16 v[56:59], v[192:195], v[152:155], v[56:59]
	v_mfma_f32_16x16x32_f16 v[36:39], v[184:187], v[160:163], v[36:39]
	v_mfma_f32_16x16x32_f16 v[40:43], v[192:195], v[160:163], v[40:43]
	v_mfma_f32_16x16x32_f16 v[20:23], v[184:187], v[168:171], v[20:23]
	v_mfma_f32_16x16x32_f16 v[24:27], v[192:195], v[168:171], v[24:27]
	v_mfma_f32_16x16x32_f16 v[8:11], v[184:187], v[176:179], v[8:11]
	v_mfma_f32_16x16x32_f16 v[4:7], v[192:195], v[176:179], v[4:7]
	v_add_u32_e32 v1, s99, v238
	s_barrier
	ds_read_b128 v[132:135], v1
	ds_read_b128 v[136:139], v1 offset:1024
	ds_read_b128 v[140:143], v1 offset:2048
	ds_read_b128 v[144:147], v1 offset:3072
	s_add_u32 s10, s10, s28
	s_addc_u32 s11, s11, s29
	s_mov_b32 m0, s79
	v_lshl_add_u64 v[180:181], s[10:11], 0, v[200:201]
	ds_read_b128 v[148:151], v240 offset:32768
	ds_read_b128 v[152:155], v240 offset:33792
	ds_read_b128 v[156:159], v240 offset:34816
	ds_read_b128 v[160:163], v240 offset:35840
	ds_read_b128 v[164:167], v240 offset:36864
	ds_read_b128 v[168:171], v240 offset:37888
	ds_read_b128 v[172:175], v240 offset:38912
	ds_read_b128 v[176:179], v240 offset:39936
	global_load_lds_dwordx4 v[180:181], off
	v_lshl_add_u64 v[180:181], s[10:11], 0, v[202:203]
	s_mov_b32 m0, s60
	s_nop 0
	global_load_lds_dwordx4 v[180:181], off
	s_waitcnt lgkmcnt(8)
	s_waitcnt vmcnt(10)
	s_barrier
	s_waitcnt lgkmcnt(0)
	s_waitcnt lgkmcnt(0)
	v_mfma_f32_16x16x32_f16 v[124:127], v[132:135], v[148:151], v[124:127]
	v_mfma_f32_16x16x32_f16 v[128:131], v[140:143], v[148:151], v[128:131]
	v_mfma_f32_16x16x32_f16 v[108:111], v[132:135], v[156:159], v[108:111]
	v_mfma_f32_16x16x32_f16 v[112:115], v[140:143], v[156:159], v[112:115]
	v_mfma_f32_16x16x32_f16 v[92:95], v[132:135], v[164:167], v[92:95]
	v_mfma_f32_16x16x32_f16 v[96:99], v[140:143], v[164:167], v[96:99]
	v_mfma_f32_16x16x32_f16 v[76:79], v[132:135], v[172:175], v[76:79]
	v_mfma_f32_16x16x32_f16 v[80:83], v[140:143], v[172:175], v[80:83]
	v_mfma_f32_16x16x32_f16 v[124:127], v[136:139], v[152:155], v[124:127]
	v_mfma_f32_16x16x32_f16 v[128:131], v[144:147], v[152:155], v[128:131]
	v_mfma_f32_16x16x32_f16 v[108:111], v[136:139], v[160:163], v[108:111]
	v_mfma_f32_16x16x32_f16 v[112:115], v[144:147], v[160:163], v[112:115]
	v_mfma_f32_16x16x32_f16 v[92:95], v[136:139], v[168:171], v[92:95]
	v_mfma_f32_16x16x32_f16 v[96:99], v[144:147], v[168:171], v[96:99]
	v_mfma_f32_16x16x32_f16 v[76:79], v[136:139], v[176:179], v[76:79]
	v_mfma_f32_16x16x32_f16 v[80:83], v[144:147], v[176:179], v[80:83]
	s_barrier
	s_add_i32 s10, 0, 0x1c000
	s_add_i32 s11, s99, s72
	v_add_u32_e32 v1, s10, v238
	v_lshl_add_u64 v[210:211], v[210:211], 0, s[86:87]
	s_mov_b32 m0, s11
	ds_read_b128 v[180:183], v1
	ds_read_b128 v[184:187], v1 offset:1024
	ds_read_b128 v[188:191], v1 offset:2048
	ds_read_b128 v[192:195], v1 offset:3072
	global_load_lds_dwordx4 v[210:211], off
	v_lshl_add_u64 v[210:211], v[212:213], 0, s[86:87]
	s_add_i32 m0, s11, 0x2000
	s_nop 0
	global_load_lds_dwordx4 v[210:211], off
	s_waitcnt vmcnt(10)
	s_barrier
	s_waitcnt lgkmcnt(0)
	s_waitcnt lgkmcnt(0)
	v_mfma_f32_16x16x32_f16 v[116:119], v[180:183], v[148:151], v[116:119]
	v_mfma_f32_16x16x32_f16 v[120:123], v[188:191], v[148:151], v[120:123]
	v_mfma_f32_16x16x32_f16 v[100:103], v[180:183], v[156:159], v[100:103]
	v_mfma_f32_16x16x32_f16 v[104:107], v[188:191], v[156:159], v[104:107]
	v_mfma_f32_16x16x32_f16 v[84:87], v[180:183], v[164:167], v[84:87]
	v_mfma_f32_16x16x32_f16 v[88:91], v[188:191], v[164:167], v[88:91]
	v_mfma_f32_16x16x32_f16 v[68:71], v[180:183], v[172:175], v[68:71]
	v_mfma_f32_16x16x32_f16 v[72:75], v[188:191], v[172:175], v[72:75]
	v_mfma_f32_16x16x32_f16 v[116:119], v[184:187], v[152:155], v[116:119]
	v_mfma_f32_16x16x32_f16 v[120:123], v[192:195], v[152:155], v[120:123]
	v_mfma_f32_16x16x32_f16 v[100:103], v[184:187], v[160:163], v[100:103]
	v_mfma_f32_16x16x32_f16 v[104:107], v[192:195], v[160:163], v[104:107]
	v_mfma_f32_16x16x32_f16 v[84:87], v[184:187], v[168:171], v[84:87]
	v_mfma_f32_16x16x32_f16 v[88:91], v[192:195], v[168:171], v[88:91]
	v_mfma_f32_16x16x32_f16 v[68:71], v[184:187], v[176:179], v[68:71]
	v_mfma_f32_16x16x32_f16 v[72:75], v[192:195], v[176:179], v[72:75]
	s_mov_b32 m0, s77
	v_lshl_add_u64 v[210:211], v[214:215], 0, s[86:87]
	s_barrier
	ds_read_b128 v[148:151], v240 offset:49152
	ds_read_b128 v[152:155], v240 offset:50176
	ds_read_b128 v[156:159], v240 offset:51200
	ds_read_b128 v[160:163], v240 offset:52224
	ds_read_b128 v[164:167], v240 offset:53248
	ds_read_b128 v[168:171], v240 offset:54272
	ds_read_b128 v[172:175], v240 offset:55296
	ds_read_b128 v[176:179], v240 offset:56320
	global_load_lds_dwordx4 v[210:211], off
	v_lshl_add_u64 v[210:211], v[216:217], 0, s[86:87]
	s_mov_b32 m0, s64
	s_nop 0
	global_load_lds_dwordx4 v[210:211], off
	s_barrier
	s_waitcnt lgkmcnt(0)
	s_waitcnt lgkmcnt(0)
	v_mfma_f32_16x16x32_f16 v[60:63], v[132:135], v[148:151], v[60:63]
	v_mfma_f32_16x16x32_f16 v[64:67], v[140:143], v[148:151], v[64:67]
	v_mfma_f32_16x16x32_f16 v[44:47], v[132:135], v[156:159], v[44:47]
	v_mfma_f32_16x16x32_f16 v[48:51], v[140:143], v[156:159], v[48:51]
	v_mfma_f32_16x16x32_f16 v[28:31], v[132:135], v[164:167], v[28:31]
	v_mfma_f32_16x16x32_f16 v[32:35], v[140:143], v[164:167], v[32:35]
	v_mfma_f32_16x16x32_f16 v[12:15], v[132:135], v[172:175], v[12:15]
	v_mfma_f32_16x16x32_f16 v[16:19], v[140:143], v[172:175], v[16:19]
	v_mfma_f32_16x16x32_f16 v[60:63], v[136:139], v[152:155], v[60:63]
	v_mfma_f32_16x16x32_f16 v[64:67], v[144:147], v[152:155], v[64:67]
	v_mfma_f32_16x16x32_f16 v[44:47], v[136:139], v[160:163], v[44:47]
	v_mfma_f32_16x16x32_f16 v[48:51], v[144:147], v[160:163], v[48:51]
	v_mfma_f32_16x16x32_f16 v[28:31], v[136:139], v[168:171], v[28:31]
	v_mfma_f32_16x16x32_f16 v[32:35], v[144:147], v[168:171], v[32:35]
	v_mfma_f32_16x16x32_f16 v[12:15], v[136:139], v[176:179], v[12:15]
	v_mfma_f32_16x16x32_f16 v[16:19], v[144:147], v[176:179], v[16:19]
	s_barrier
	s_add_i32 s10, s10, s72
	v_lshl_add_u64 v[132:133], v[218:219], 0, s[86:87]
	s_mov_b32 m0, s10
	s_nop 0
	global_load_lds_dwordx4 v[132:133], off
	v_lshl_add_u64 v[132:133], v[220:221], 0, s[86:87]
	s_add_i32 m0, s10, 0x2000
	s_nop 0
	global_load_lds_dwordx4 v[132:133], off
	s_waitcnt vmcnt(10)
	s_barrier
	v_mfma_f32_16x16x32_f16 v[52:55], v[180:183], v[148:151], v[52:55]
	v_mfma_f32_16x16x32_f16 v[56:59], v[188:191], v[148:151], v[56:59]
	v_mfma_f32_16x16x32_f16 v[36:39], v[180:183], v[156:159], v[36:39]
	v_mfma_f32_16x16x32_f16 v[40:43], v[188:191], v[156:159], v[40:43]
	v_mfma_f32_16x16x32_f16 v[20:23], v[180:183], v[164:167], v[20:23]
	v_mfma_f32_16x16x32_f16 v[24:27], v[188:191], v[164:167], v[24:27]
	v_mfma_f32_16x16x32_f16 v[8:11], v[180:183], v[172:175], v[8:11]
	v_mfma_f32_16x16x32_f16 v[4:7], v[188:191], v[172:175], v[4:7]
	v_mfma_f32_16x16x32_f16 v[52:55], v[184:187], v[152:155], v[52:55]
	v_mfma_f32_16x16x32_f16 v[56:59], v[192:195], v[152:155], v[56:59]
	v_mfma_f32_16x16x32_f16 v[36:39], v[184:187], v[160:163], v[36:39]
	v_mfma_f32_16x16x32_f16 v[40:43], v[192:195], v[160:163], v[40:43]
	v_mfma_f32_16x16x32_f16 v[20:23], v[184:187], v[168:171], v[20:23]
	v_mfma_f32_16x16x32_f16 v[24:27], v[192:195], v[168:171], v[24:27]
	v_mfma_f32_16x16x32_f16 v[8:11], v[184:187], v[176:179], v[8:11]
	v_mfma_f32_16x16x32_f16 v[4:7], v[192:195], v[176:179], v[4:7]
	s_add_u32 s4, s4, 0x100
	s_addc_u32 s5, s5, 0
	s_add_u32 s1, s1, 0x100
	s_addc_u32 vcc_lo, vcc_lo, 0
	s_cmp_ge_i32 vcc_hi, s67
	s_mov_b32 s10, vcc_hi
	s_barrier
	s_cbranch_scc1 .LBB0_377
	s_branch .LBB0_376
.Lk_goB:
	s_add_i32 vcc_hi, s10, 2
	s_add_u32 s56, s4, 0x80
	s_addc_u32 s11, s5, 0
	s_add_i32 s98, 0, 0x10000
	v_add_u32_e32 v1, s98, v238
	ds_read_b128 v[132:135], v1
	ds_read_b128 v[136:139], v1 offset:1024
	ds_read_b128 v[140:143], v1 offset:2048
	ds_read_b128 v[144:147], v1 offset:3072
	s_cmp_eq_u32 s75, s10
	s_cselect_b32 s10, s50, s56
	s_cselect_b32 s11, s51, s11
	s_cselect_b32 s57, s97, vcc_lo
	s_cselect_b32 s56, s96, s1
	v_lshl_add_u64 v[180:181], s[4:5], 0, v[206:207]
	s_add_i32 m0, s73, 0xc000
	ds_read_b128 v[148:151], v240
	ds_read_b128 v[152:155], v240 offset:1024
	ds_read_b128 v[156:159], v240 offset:2048
	ds_read_b128 v[160:163], v240 offset:3072
	ds_read_b128 v[164:167], v240 offset:4096
	ds_read_b128 v[168:171], v240 offset:5120
	ds_read_b128 v[172:175], v240 offset:6144
	ds_read_b128 v[176:179], v240 offset:7168
	global_load_lds_dwordx4 v[180:181], off
	v_lshl_add_u64 v[180:181], s[4:5], 0, v[208:209]
	s_add_i32 m0, s73, 0xe000
	s_nop 0
	global_load_lds_dwordx4 v[180:181], off
	s_waitcnt lgkmcnt(8)
	s_waitcnt vmcnt(18)
	s_barrier
	s_waitcnt lgkmcnt(0)
	s_waitcnt lgkmcnt(0)
	v_mfma_f32_16x16x32_f16 v[124:127], v[132:135], v[148:151], 0
	v_mfma_f32_16x16x32_f16 v[128:131], v[140:143], v[148:151], 0
	v_mfma_f32_16x16x32_f16 v[108:111], v[132:135], v[156:159], 0
	v_mfma_f32_16x16x32_f16 v[112:115], v[140:143], v[156:159], 0
	v_mfma_f32_16x16x32_f16 v[92:95], v[132:135], v[164:167], 0
	v_mfma_f32_16x16x32_f16 v[96:99], v[140:143], v[164:167], 0
	v_mfma_f32_16x16x32_f16 v[76:79], v[132:135], v[172:175], 0
	v_mfma_f32_16x16x32_f16 v[80:83], v[140:143], v[172:175], 0
	v_mfma_f32_16x16x32_f16 v[124:127], v[136:139], v[152:155], v[124:127]
	v_mfma_f32_16x16x32_f16 v[128:131], v[144:147], v[152:155], v[128:131]
	v_mfma_f32_16x16x32_f16 v[108:111], v[136:139], v[160:163], v[108:111]
	v_mfma_f32_16x16x32_f16 v[112:115], v[144:147], v[160:163], v[112:115]
	v_mfma_f32_16x16x32_f16 v[92:95], v[136:139], v[168:171], v[92:95]
	v_mfma_f32_16x16x32_f16 v[96:99], v[144:147], v[168:171], v[96:99]
	v_mfma_f32_16x16x32_f16 v[76:79], v[136:139], v[176:179], v[76:79]
	v_mfma_f32_16x16x32_f16 v[80:83], v[144:147], v[176:179], v[80:83]
	s_barrier
	s_add_i32 s98, s98, s72
	v_add_u32_e32 v1, s58, v238
	v_lshl_add_u64 v[210:211], s[56:57], 0, v[200:201]
	s_mov_b32 m0, s98
	ds_read_b128 v[180:183], v1
	ds_read_b128 v[184:187], v1 offset:1024
	ds_read_b128 v[188:191], v1 offset:2048
	ds_read_b128 v[192:195], v1 offset:3072
	global_load_lds_dwordx4 v[210:211], off
	v_lshl_add_u64 v[212:213], s[56:57], 0, v[202:203]
	s_add_i32 m0, s98, 0x2000
	s_nop 0
	global_load_lds_dwordx4 v[212:213], off
	s_waitcnt vmcnt(18)
	s_barrier
	s_waitcnt lgkmcnt(0)
	s_waitcnt lgkmcnt(0)
	v_mfma_f32_16x16x32_f16 v[116:119], v[180:183], v[148:151], 0
	v_mfma_f32_16x16x32_f16 v[120:123], v[188:191], v[148:151], 0
	v_mfma_f32_16x16x32_f16 v[100:103], v[180:183], v[156:159], 0
	v_mfma_f32_16x16x32_f16 v[104:107], v[188:191], v[156:159], 0
	v_mfma_f32_16x16x32_f16 v[84:87], v[180:183], v[164:167], 0
	v_mfma_f32_16x16x32_f16 v[88:91], v[188:191], v[164:167], 0
	v_mfma_f32_16x16x32_f16 v[68:71], v[180:183], v[172:175], 0
	v_mfma_f32_16x16x32_f16 v[72:75], v[188:191], v[172:175], 0
	v_mfma_f32_16x16x32_f16 v[116:119], v[184:187], v[152:155], v[116:119]
	v_mfma_f32_16x16x32_f16 v[120:123], v[192:195], v[152:155], v[120:123]
	v_mfma_f32_16x16x32_f16 v[100:103], v[184:187], v[160:163], v[100:103]
	v_mfma_f32_16x16x32_f16 v[104:107], v[192:195], v[160:163], v[104:107]
	v_mfma_f32_16x16x32_f16 v[84:87], v[184:187], v[168:171], v[84:87]
	v_mfma_f32_16x16x32_f16 v[88:91], v[192:195], v[168:171], v[88:91]
	v_mfma_f32_16x16x32_f16 v[68:71], v[184:187], v[176:179], v[68:71]
	v_mfma_f32_16x16x32_f16 v[72:75], v[192:195], v[176:179], v[72:75]
	s_mov_b32 m0, s73
	v_lshl_add_u64 v[214:215], s[10:11], 0, v[200:201]
	s_barrier
	ds_read_b128 v[148:151], v240 offset:16384
	ds_read_b128 v[152:155], v240 offset:17408
	ds_read_b128 v[156:159], v240 offset:18432
	ds_read_b128 v[160:163], v240 offset:19456
	ds_read_b128 v[164:167], v240 offset:20480
	ds_read_b128 v[168:171], v240 offset:21504
	ds_read_b128 v[172:175], v240 offset:22528
	ds_read_b128 v[176:179], v240 offset:23552
	global_load_lds_dwordx4 v[214:215], off
	v_lshl_add_u64 v[216:217], s[10:11], 0, v[202:203]
	s_mov_b32 m0, s78
	s_nop 0
	global_load_lds_dwordx4 v[216:217], off
	s_barrier
	s_waitcnt lgkmcnt(0)
	s_waitcnt lgkmcnt(0)
	v_mfma_f32_16x16x32_f16 v[60:63], v[132:135], v[148:151], 0
	v_mfma_f32_16x16x32_f16 v[64:67], v[140:143], v[148:151], 0
	v_mfma_f32_16x16x32_f16 v[44:47], v[132:135], v[156:159], 0
	v_mfma_f32_16x16x32_f16 v[48:51], v[140:143], v[156:159], 0
	v_mfma_f32_16x16x32_f16 v[28:31], v[132:135], v[164:167], 0
	v_mfma_f32_16x16x32_f16 v[32:35], v[140:143], v[164:167], 0
	v_mfma_f32_16x16x32_f16 v[12:15], v[132:135], v[172:175], 0
	v_mfma_f32_16x16x32_f16 v[16:19], v[140:143], v[172:175], 0
	v_mfma_f32_16x16x32_f16 v[60:63], v[136:139], v[152:155], v[60:63]
	v_mfma_f32_16x16x32_f16 v[64:67], v[144:147], v[152:155], v[64:67]
	v_mfma_f32_16x16x32_f16 v[44:47], v[136:139], v[160:163], v[44:47]
	v_mfma_f32_16x16x32_f16 v[48:51], v[144:147], v[160:163], v[48:51]
	v_mfma_f32_16x16x32_f16 v[28:31], v[136:139], v[168:171], v[28:31]
	v_mfma_f32_16x16x32_f16 v[32:35], v[144:147], v[168:171], v[32:35]
	v_mfma_f32_16x16x32_f16 v[12:15], v[136:139], v[176:179], v[12:15]
	v_mfma_f32_16x16x32_f16 v[16:19], v[144:147], v[176:179], v[16:19]
	s_barrier
	s_add_u32 s56, s56, s28
	s_addc_u32 s57, s57, s29
	s_add_i32 s98, s58, s72
	v_lshl_add_u64 v[218:219], s[56:57], 0, v[200:201]
	s_mov_b32 m0, s98
	v_lshl_add_u64 v[220:221], s[56:57], 0, v[202:203]
	global_load_lds_dwordx4 v[218:219], off
	s_add_i32 m0, s98, 0x2000
	s_nop 0
	global_load_lds_dwordx4 v[220:221], off
	s_waitcnt vmcnt(18)
	s_barrier
	v_mfma_f32_16x16x32_f16 v[52:55], v[180:183], v[148:151], 0
	v_mfma_f32_16x16x32_f16 v[56:59], v[188:191], v[148:151], 0
	v_mfma_f32_16x16x32_f16 v[36:39], v[180:183], v[156:159], 0
	v_mfma_f32_16x16x32_f16 v[40:43], v[188:191], v[156:159], 0
	v_mfma_f32_16x16x32_f16 v[20:23], v[180:183], v[164:167], 0
	v_mfma_f32_16x16x32_f16 v[24:27], v[188:191], v[164:167], 0
	v_mfma_f32_16x16x32_f16 v[8:11], v[180:183], v[172:175], 0
	v_mfma_f32_16x16x32_f16 v[4:7], v[188:191], v[172:175], 0
	v_mfma_f32_16x16x32_f16 v[52:55], v[184:187], v[152:155], v[52:55]
	v_mfma_f32_16x16x32_f16 v[56:59], v[192:195], v[152:155], v[56:59]
	v_mfma_f32_16x16x32_f16 v[36:39], v[184:187], v[160:163], v[36:39]
	v_mfma_f32_16x16x32_f16 v[40:43], v[192:195], v[160:163], v[40:43]
	v_mfma_f32_16x16x32_f16 v[20:23], v[184:187], v[168:171], v[20:23]
	v_mfma_f32_16x16x32_f16 v[24:27], v[192:195], v[168:171], v[24:27]
	v_mfma_f32_16x16x32_f16 v[8:11], v[184:187], v[176:179], v[8:11]
	v_mfma_f32_16x16x32_f16 v[4:7], v[192:195], v[176:179], v[4:7]
	v_add_u32_e32 v1, s99, v238
	s_barrier
	ds_read_b128 v[132:135], v1
	ds_read_b128 v[136:139], v1 offset:1024
	ds_read_b128 v[140:143], v1 offset:2048
	ds_read_b128 v[144:147], v1 offset:3072
	s_add_u32 s10, s10, s28
	s_addc_u32 s11, s11, s29
	s_mov_b32 m0, s79
	v_lshl_add_u64 v[180:181], s[10:11], 0, v[200:201]
	ds_read_b128 v[148:151], v240 offset:32768
	ds_read_b128 v[152:155], v240 offset:33792
	ds_read_b128 v[156:159], v240 offset:34816
	ds_read_b128 v[160:163], v240 offset:35840
	ds_read_b128 v[164:167], v240 offset:36864
	ds_read_b128 v[168:171], v240 offset:37888
	ds_read_b128 v[172:175], v240 offset:38912
	ds_read_b128 v[176:179], v240 offset:39936
	global_load_lds_dwordx4 v[180:181], off
	v_lshl_add_u64 v[180:181], s[10:11], 0, v[202:203]
	s_mov_b32 m0, s60
	s_nop 0
	global_load_lds_dwordx4 v[180:181], off
	s_waitcnt lgkmcnt(8)
	s_waitcnt vmcnt(18)
	s_barrier
	s_waitcnt lgkmcnt(0)
	s_waitcnt lgkmcnt(0)
	v_mfma_f32_16x16x32_f16 v[124:127], v[132:135], v[148:151], v[124:127]
	v_mfma_f32_16x16x32_f16 v[128:131], v[140:143], v[148:151], v[128:131]
	v_mfma_f32_16x16x32_f16 v[108:111], v[132:135], v[156:159], v[108:111]
	v_mfma_f32_16x16x32_f16 v[112:115], v[140:143], v[156:159], v[112:115]
	v_mfma_f32_16x16x32_f16 v[92:95], v[132:135], v[164:167], v[92:95]
	v_mfma_f32_16x16x32_f16 v[96:99], v[140:143], v[164:167], v[96:99]
	v_mfma_f32_16x16x32_f16 v[76:79], v[132:135], v[172:175], v[76:79]
	v_mfma_f32_16x16x32_f16 v[80:83], v[140:143], v[172:175], v[80:83]
	v_mfma_f32_16x16x32_f16 v[124:127], v[136:139], v[152:155], v[124:127]
	v_mfma_f32_16x16x32_f16 v[128:131], v[144:147], v[152:155], v[128:131]
	v_mfma_f32_16x16x32_f16 v[108:111], v[136:139], v[160:163], v[108:111]
	v_mfma_f32_16x16x32_f16 v[112:115], v[144:147], v[160:163], v[112:115]
	v_mfma_f32_16x16x32_f16 v[92:95], v[136:139], v[168:171], v[92:95]
	v_mfma_f32_16x16x32_f16 v[96:99], v[144:147], v[168:171], v[96:99]
	v_mfma_f32_16x16x32_f16 v[76:79], v[136:139], v[176:179], v[76:79]
	v_mfma_f32_16x16x32_f16 v[80:83], v[144:147], v[176:179], v[80:83]
	s_barrier
	s_add_i32 s10, 0, 0x1c000
	s_add_i32 s11, s99, s72
	v_add_u32_e32 v1, s10, v238
	v_lshl_add_u64 v[210:211], v[210:211], 0, s[86:87]
	s_mov_b32 m0, s11
	ds_read_b128 v[180:183], v1
	ds_read_b128 v[184:187], v1 offset:1024
	ds_read_b128 v[188:191], v1 offset:2048
	ds_read_b128 v[192:195], v1 offset:3072
	global_load_lds_dwordx4 v[210:211], off
	v_lshl_add_u64 v[210:211], v[212:213], 0, s[86:87]
	s_add_i32 m0, s11, 0x2000
	s_nop 0
	global_load_lds_dwordx4 v[210:211], off
	s_waitcnt vmcnt(18)
	s_barrier
	s_waitcnt lgkmcnt(0)
	s_waitcnt lgkmcnt(0)
	v_mfma_f32_16x16x32_f16 v[116:119], v[180:183], v[148:151], v[116:119]
	v_mfma_f32_16x16x32_f16 v[120:123], v[188:191], v[148:151], v[120:123]
	v_mfma_f32_16x16x32_f16 v[100:103], v[180:183], v[156:159], v[100:103]
	v_mfma_f32_16x16x32_f16 v[104:107], v[188:191], v[156:159], v[104:107]
	v_mfma_f32_16x16x32_f16 v[84:87], v[180:183], v[164:167], v[84:87]
	v_mfma_f32_16x16x32_f16 v[88:91], v[188:191], v[164:167], v[88:91]
	v_mfma_f32_16x16x32_f16 v[68:71], v[180:183], v[172:175], v[68:71]
	v_mfma_f32_16x16x32_f16 v[72:75], v[188:191], v[172:175], v[72:75]
	v_mfma_f32_16x16x32_f16 v[116:119], v[184:187], v[152:155], v[116:119]
	v_mfma_f32_16x16x32_f16 v[120:123], v[192:195], v[152:155], v[120:123]
	v_mfma_f32_16x16x32_f16 v[100:103], v[184:187], v[160:163], v[100:103]
	v_mfma_f32_16x16x32_f16 v[104:107], v[192:195], v[160:163], v[104:107]
	v_mfma_f32_16x16x32_f16 v[84:87], v[184:187], v[168:171], v[84:87]
	v_mfma_f32_16x16x32_f16 v[88:91], v[192:195], v[168:171], v[88:91]
	v_mfma_f32_16x16x32_f16 v[68:71], v[184:187], v[176:179], v[68:71]
	v_mfma_f32_16x16x32_f16 v[72:75], v[192:195], v[176:179], v[72:75]
	s_mov_b32 m0, s77
	v_lshl_add_u64 v[210:211], v[214:215], 0, s[86:87]
	s_barrier
	ds_read_b128 v[148:151], v240 offset:49152
	ds_read_b128 v[152:155], v240 offset:50176
	ds_read_b128 v[156:159], v240 offset:51200
	ds_read_b128 v[160:163], v240 offset:52224
	ds_read_b128 v[164:167], v240 offset:53248
	ds_read_b128 v[168:171], v240 offset:54272
	ds_read_b128 v[172:175], v240 offset:55296
	ds_read_b128 v[176:179], v240 offset:56320
	global_load_lds_dwordx4 v[210:211], off
	v_lshl_add_u64 v[210:211], v[216:217], 0, s[86:87]
	s_mov_b32 m0, s64
	s_nop 0
	global_load_lds_dwordx4 v[210:211], off
	s_barrier
	s_waitcnt lgkmcnt(0)
	s_waitcnt lgkmcnt(0)
	v_mfma_f32_16x16x32_f16 v[60:63], v[132:135], v[148:151], v[60:63]
	v_mfma_f32_16x16x32_f16 v[64:67], v[140:143], v[148:151], v[64:67]
	v_mfma_f32_16x16x32_f16 v[44:47], v[132:135], v[156:159], v[44:47]
	v_mfma_f32_16x16x32_f16 v[48:51], v[140:143], v[156:159], v[48:51]
	v_mfma_f32_16x16x32_f16 v[28:31], v[132:135], v[164:167], v[28:31]
	v_mfma_f32_16x16x32_f16 v[32:35], v[140:143], v[164:167], v[32:35]
	v_mfma_f32_16x16x32_f16 v[12:15], v[132:135], v[172:175], v[12:15]
	v_mfma_f32_16x16x32_f16 v[16:19], v[140:143], v[172:175], v[16:19]
	v_mfma_f32_16x16x32_f16 v[60:63], v[136:139], v[152:155], v[60:63]
	v_mfma_f32_16x16x32_f16 v[64:67], v[144:147], v[152:155], v[64:67]
	v_mfma_f32_16x16x32_f16 v[44:47], v[136:139], v[160:163], v[44:47]
	v_mfma_f32_16x16x32_f16 v[48:51], v[144:147], v[160:163], v[48:51]
	v_mfma_f32_16x16x32_f16 v[28:31], v[136:139], v[168:171], v[28:31]
	v_mfma_f32_16x16x32_f16 v[32:35], v[144:147], v[168:171], v[32:35]
	v_mfma_f32_16x16x32_f16 v[12:15], v[136:139], v[176:179], v[12:15]
	v_mfma_f32_16x16x32_f16 v[16:19], v[144:147], v[176:179], v[16:19]
	s_barrier
	s_add_i32 s10, s10, s72
	v_lshl_add_u64 v[132:133], v[218:219], 0, s[86:87]
	s_mov_b32 m0, s10
	s_nop 0
	global_load_lds_dwordx4 v[132:133], off
	v_lshl_add_u64 v[132:133], v[220:221], 0, s[86:87]
	s_add_i32 m0, s10, 0x2000
	s_nop 0
	global_load_lds_dwordx4 v[132:133], off
	s_waitcnt vmcnt(18)
	s_barrier
	v_mfma_f32_16x16x32_f16 v[52:55], v[180:183], v[148:151], v[52:55]
	v_mfma_f32_16x16x32_f16 v[56:59], v[188:191], v[148:151], v[56:59]
	v_mfma_f32_16x16x32_f16 v[36:39], v[180:183], v[156:159], v[36:39]
	v_mfma_f32_16x16x32_f16 v[40:43], v[188:191], v[156:159], v[40:43]
	v_mfma_f32_16x16x32_f16 v[20:23], v[180:183], v[164:167], v[20:23]
	v_mfma_f32_16x16x32_f16 v[24:27], v[188:191], v[164:167], v[24:27]
	v_mfma_f32_16x16x32_f16 v[8:11], v[180:183], v[172:175], v[8:11]
	v_mfma_f32_16x16x32_f16 v[4:7], v[188:191], v[172:175], v[4:7]
	v_mfma_f32_16x16x32_f16 v[52:55], v[184:187], v[152:155], v[52:55]
	v_mfma_f32_16x16x32_f16 v[56:59], v[192:195], v[152:155], v[56:59]
	v_mfma_f32_16x16x32_f16 v[36:39], v[184:187], v[160:163], v[36:39]
	v_mfma_f32_16x16x32_f16 v[40:43], v[192:195], v[160:163], v[40:43]
	v_mfma_f32_16x16x32_f16 v[20:23], v[184:187], v[168:171], v[20:23]
	v_mfma_f32_16x16x32_f16 v[24:27], v[192:195], v[168:171], v[24:27]
	v_mfma_f32_16x16x32_f16 v[8:11], v[184:187], v[176:179], v[8:11]
	v_mfma_f32_16x16x32_f16 v[4:7], v[192:195], v[176:179], v[4:7]
	s_add_u32 s4, s4, 0x100
	s_addc_u32 s5, s5, 0
	s_add_u32 s1, s1, 0x100
	s_addc_u32 vcc_lo, vcc_lo, 0
	s_cmp_ge_i32 vcc_hi, s67
	s_mov_b32 s10, vcc_hi
	s_barrier
	s_cbranch_scc1 .LBB0_377
.LBB0_376:
	s_add_i32 vcc_hi, s10, 2
	s_add_u32 s56, s4, 0x80
	s_addc_u32 s11, s5, 0
	s_add_i32 s98, 0, 0x10000
	v_add_u32_e32 v1, s98, v238
	ds_read_b128 v[132:135], v1
	ds_read_b128 v[136:139], v1 offset:1024
	ds_read_b128 v[140:143], v1 offset:2048
	ds_read_b128 v[144:147], v1 offset:3072
	s_cmp_eq_u32 s75, s10
	s_cselect_b32 s10, s50, s56
	s_cselect_b32 s11, s51, s11
	s_cselect_b32 s57, s97, vcc_lo
	s_cselect_b32 s56, s96, s1
	v_lshl_add_u64 v[180:181], s[4:5], 0, v[206:207]
	s_add_i32 m0, s73, 0xc000
	ds_read_b128 v[148:151], v240
	ds_read_b128 v[152:155], v240 offset:1024
	ds_read_b128 v[156:159], v240 offset:2048
	ds_read_b128 v[160:163], v240 offset:3072
	ds_read_b128 v[164:167], v240 offset:4096
	ds_read_b128 v[168:171], v240 offset:5120
	ds_read_b128 v[172:175], v240 offset:6144
	ds_read_b128 v[176:179], v240 offset:7168
	global_load_lds_dwordx4 v[180:181], off
	v_lshl_add_u64 v[180:181], s[4:5], 0, v[208:209]
	s_add_i32 m0, s73, 0xe000
	s_nop 0
	global_load_lds_dwordx4 v[180:181], off
	s_waitcnt lgkmcnt(8)
	s_waitcnt vmcnt(10)
	s_barrier
	s_waitcnt lgkmcnt(0)
	s_waitcnt lgkmcnt(0)
	v_mfma_f32_16x16x32_f16 v[124:127], v[132:135], v[148:151], v[124:127]
	v_mfma_f32_16x16x32_f16 v[128:131], v[140:143], v[148:151], v[128:131]
	v_mfma_f32_16x16x32_f16 v[108:111], v[132:135], v[156:159], v[108:111]
	v_mfma_f32_16x16x32_f16 v[112:115], v[140:143], v[156:159], v[112:115]
	v_mfma_f32_16x16x32_f16 v[92:95], v[132:135], v[164:167], v[92:95]
	v_mfma_f32_16x16x32_f16 v[96:99], v[140:143], v[164:167], v[96:99]
	v_mfma_f32_16x16x32_f16 v[76:79], v[132:135], v[172:175], v[76:79]
	v_mfma_f32_16x16x32_f16 v[80:83], v[140:143], v[172:175], v[80:83]
	v_mfma_f32_16x16x32_f16 v[124:127], v[136:139], v[152:155], v[124:127]
	v_mfma_f32_16x16x32_f16 v[128:131], v[144:147], v[152:155], v[128:131]
	v_mfma_f32_16x16x32_f16 v[108:111], v[136:139], v[160:163], v[108:111]
	v_mfma_f32_16x16x32_f16 v[112:115], v[144:147], v[160:163], v[112:115]
	v_mfma_f32_16x16x32_f16 v[92:95], v[136:139], v[168:171], v[92:95]
	v_mfma_f32_16x16x32_f16 v[96:99], v[144:147], v[168:171], v[96:99]
	v_mfma_f32_16x16x32_f16 v[76:79], v[136:139], v[176:179], v[76:79]
	v_mfma_f32_16x16x32_f16 v[80:83], v[144:147], v[176:179], v[80:83]
	s_barrier
	s_add_i32 s98, s98, s72
	v_add_u32_e32 v1, s58, v238
	v_lshl_add_u64 v[210:211], s[56:57], 0, v[200:201]
	s_mov_b32 m0, s98
	ds_read_b128 v[180:183], v1
	ds_read_b128 v[184:187], v1 offset:1024
	ds_read_b128 v[188:191], v1 offset:2048
	ds_read_b128 v[192:195], v1 offset:3072
	global_load_lds_dwordx4 v[210:211], off
	v_lshl_add_u64 v[212:213], s[56:57], 0, v[202:203]
	s_add_i32 m0, s98, 0x2000
	s_nop 0
	global_load_lds_dwordx4 v[212:213], off
	s_waitcnt vmcnt(10)
	s_barrier
	s_waitcnt lgkmcnt(0)
	s_waitcnt lgkmcnt(0)
	v_mfma_f32_16x16x32_f16 v[116:119], v[180:183], v[148:151], v[116:119]
	v_mfma_f32_16x16x32_f16 v[120:123], v[188:191], v[148:151], v[120:123]
	v_mfma_f32_16x16x32_f16 v[100:103], v[180:183], v[156:159], v[100:103]
	v_mfma_f32_16x16x32_f16 v[104:107], v[188:191], v[156:159], v[104:107]
	v_mfma_f32_16x16x32_f16 v[84:87], v[180:183], v[164:167], v[84:87]
	v_mfma_f32_16x16x32_f16 v[88:91], v[188:191], v[164:167], v[88:91]
	v_mfma_f32_16x16x32_f16 v[68:71], v[180:183], v[172:175], v[68:71]
	v_mfma_f32_16x16x32_f16 v[72:75], v[188:191], v[172:175], v[72:75]
	v_mfma_f32_16x16x32_f16 v[116:119], v[184:187], v[152:155], v[116:119]
	v_mfma_f32_16x16x32_f16 v[120:123], v[192:195], v[152:155], v[120:123]
	v_mfma_f32_16x16x32_f16 v[100:103], v[184:187], v[160:163], v[100:103]
	v_mfma_f32_16x16x32_f16 v[104:107], v[192:195], v[160:163], v[104:107]
	v_mfma_f32_16x16x32_f16 v[84:87], v[184:187], v[168:171], v[84:87]
	v_mfma_f32_16x16x32_f16 v[88:91], v[192:195], v[168:171], v[88:91]
	v_mfma_f32_16x16x32_f16 v[68:71], v[184:187], v[176:179], v[68:71]
	v_mfma_f32_16x16x32_f16 v[72:75], v[192:195], v[176:179], v[72:75]
	s_mov_b32 m0, s73
	v_lshl_add_u64 v[214:215], s[10:11], 0, v[200:201]
	s_barrier
	ds_read_b128 v[148:151], v240 offset:16384
	ds_read_b128 v[152:155], v240 offset:17408
	ds_read_b128 v[156:159], v240 offset:18432
	ds_read_b128 v[160:163], v240 offset:19456
	ds_read_b128 v[164:167], v240 offset:20480
	ds_read_b128 v[168:171], v240 offset:21504
	ds_read_b128 v[172:175], v240 offset:22528
	ds_read_b128 v[176:179], v240 offset:23552
	global_load_lds_dwordx4 v[214:215], off
	v_lshl_add_u64 v[216:217], s[10:11], 0, v[202:203]
	s_mov_b32 m0, s78
	s_nop 0
	global_load_lds_dwordx4 v[216:217], off
	s_barrier
	s_waitcnt lgkmcnt(0)
	s_waitcnt lgkmcnt(0)
	v_mfma_f32_16x16x32_f16 v[60:63], v[132:135], v[148:151], v[60:63]
	v_mfma_f32_16x16x32_f16 v[64:67], v[140:143], v[148:151], v[64:67]
	v_mfma_f32_16x16x32_f16 v[44:47], v[132:135], v[156:159], v[44:47]
	v_mfma_f32_16x16x32_f16 v[48:51], v[140:143], v[156:159], v[48:51]
	v_mfma_f32_16x16x32_f16 v[28:31], v[132:135], v[164:167], v[28:31]
	v_mfma_f32_16x16x32_f16 v[32:35], v[140:143], v[164:167], v[32:35]
	v_mfma_f32_16x16x32_f16 v[12:15], v[132:135], v[172:175], v[12:15]
	v_mfma_f32_16x16x32_f16 v[16:19], v[140:143], v[172:175], v[16:19]
	v_mfma_f32_16x16x32_f16 v[60:63], v[136:139], v[152:155], v[60:63]
	v_mfma_f32_16x16x32_f16 v[64:67], v[144:147], v[152:155], v[64:67]
	v_mfma_f32_16x16x32_f16 v[44:47], v[136:139], v[160:163], v[44:47]
	v_mfma_f32_16x16x32_f16 v[48:51], v[144:147], v[160:163], v[48:51]
	v_mfma_f32_16x16x32_f16 v[28:31], v[136:139], v[168:171], v[28:31]
	v_mfma_f32_16x16x32_f16 v[32:35], v[144:147], v[168:171], v[32:35]
	v_mfma_f32_16x16x32_f16 v[12:15], v[136:139], v[176:179], v[12:15]
	v_mfma_f32_16x16x32_f16 v[16:19], v[144:147], v[176:179], v[16:19]
	s_barrier
	s_add_u32 s56, s56, s28
	s_addc_u32 s57, s57, s29
	s_add_i32 s98, s58, s72
	v_lshl_add_u64 v[218:219], s[56:57], 0, v[200:201]
	s_mov_b32 m0, s98
	v_lshl_add_u64 v[220:221], s[56:57], 0, v[202:203]
	global_load_lds_dwordx4 v[218:219], off
	s_add_i32 m0, s98, 0x2000
	s_nop 0
	global_load_lds_dwordx4 v[220:221], off
	s_waitcnt vmcnt(10)
	s_barrier
	v_mfma_f32_16x16x32_f16 v[52:55], v[180:183], v[148:151], v[52:55]
	v_mfma_f32_16x16x32_f16 v[56:59], v[188:191], v[148:151], v[56:59]
	v_mfma_f32_16x16x32_f16 v[36:39], v[180:183], v[156:159], v[36:39]
	v_mfma_f32_16x16x32_f16 v[40:43], v[188:191], v[156:159], v[40:43]
	v_mfma_f32_16x16x32_f16 v[20:23], v[180:183], v[164:167], v[20:23]
	v_mfma_f32_16x16x32_f16 v[24:27], v[188:191], v[164:167], v[24:27]
	v_mfma_f32_16x16x32_f16 v[8:11], v[180:183], v[172:175], v[8:11]
	v_mfma_f32_16x16x32_f16 v[4:7], v[188:191], v[172:175], v[4:7]
	v_mfma_f32_16x16x32_f16 v[52:55], v[184:187], v[152:155], v[52:55]
	v_mfma_f32_16x16x32_f16 v[56:59], v[192:195], v[152:155], v[56:59]
	v_mfma_f32_16x16x32_f16 v[36:39], v[184:187], v[160:163], v[36:39]
	v_mfma_f32_16x16x32_f16 v[40:43], v[192:195], v[160:163], v[40:43]
	v_mfma_f32_16x16x32_f16 v[20:23], v[184:187], v[168:171], v[20:23]
	v_mfma_f32_16x16x32_f16 v[24:27], v[192:195], v[168:171], v[24:27]
	v_mfma_f32_16x16x32_f16 v[8:11], v[184:187], v[176:179], v[8:11]
	v_mfma_f32_16x16x32_f16 v[4:7], v[192:195], v[176:179], v[4:7]
	v_add_u32_e32 v1, s99, v238
	s_barrier
	ds_read_b128 v[132:135], v1
	ds_read_b128 v[136:139], v1 offset:1024
	ds_read_b128 v[140:143], v1 offset:2048
	ds_read_b128 v[144:147], v1 offset:3072
	s_add_u32 s10, s10, s28
	s_addc_u32 s11, s11, s29
	s_mov_b32 m0, s79
	v_lshl_add_u64 v[180:181], s[10:11], 0, v[200:201]
	ds_read_b128 v[148:151], v240 offset:32768
	ds_read_b128 v[152:155], v240 offset:33792
	ds_read_b128 v[156:159], v240 offset:34816
	ds_read_b128 v[160:163], v240 offset:35840
	ds_read_b128 v[164:167], v240 offset:36864
	ds_read_b128 v[168:171], v240 offset:37888
	ds_read_b128 v[172:175], v240 offset:38912
	ds_read_b128 v[176:179], v240 offset:39936
	global_load_lds_dwordx4 v[180:181], off
	v_lshl_add_u64 v[180:181], s[10:11], 0, v[202:203]
	s_mov_b32 m0, s60
	s_nop 0
	global_load_lds_dwordx4 v[180:181], off
	s_waitcnt lgkmcnt(8)
	s_waitcnt vmcnt(10)
	s_barrier
	s_waitcnt lgkmcnt(0)
	s_waitcnt lgkmcnt(0)
	v_mfma_f32_16x16x32_f16 v[124:127], v[132:135], v[148:151], v[124:127]
	v_mfma_f32_16x16x32_f16 v[128:131], v[140:143], v[148:151], v[128:131]
	v_mfma_f32_16x16x32_f16 v[108:111], v[132:135], v[156:159], v[108:111]
	v_mfma_f32_16x16x32_f16 v[112:115], v[140:143], v[156:159], v[112:115]
	v_mfma_f32_16x16x32_f16 v[92:95], v[132:135], v[164:167], v[92:95]
	v_mfma_f32_16x16x32_f16 v[96:99], v[140:143], v[164:167], v[96:99]
	v_mfma_f32_16x16x32_f16 v[76:79], v[132:135], v[172:175], v[76:79]
	v_mfma_f32_16x16x32_f16 v[80:83], v[140:143], v[172:175], v[80:83]
	v_mfma_f32_16x16x32_f16 v[124:127], v[136:139], v[152:155], v[124:127]
	v_mfma_f32_16x16x32_f16 v[128:131], v[144:147], v[152:155], v[128:131]
	v_mfma_f32_16x16x32_f16 v[108:111], v[136:139], v[160:163], v[108:111]
	v_mfma_f32_16x16x32_f16 v[112:115], v[144:147], v[160:163], v[112:115]
	v_mfma_f32_16x16x32_f16 v[92:95], v[136:139], v[168:171], v[92:95]
	v_mfma_f32_16x16x32_f16 v[96:99], v[144:147], v[168:171], v[96:99]
	v_mfma_f32_16x16x32_f16 v[76:79], v[136:139], v[176:179], v[76:79]
	v_mfma_f32_16x16x32_f16 v[80:83], v[144:147], v[176:179], v[80:83]
	s_barrier
	s_add_i32 s10, 0, 0x1c000
	s_add_i32 s11, s99, s72
	v_add_u32_e32 v1, s10, v238
	v_lshl_add_u64 v[210:211], v[210:211], 0, s[86:87]
	s_mov_b32 m0, s11
	ds_read_b128 v[180:183], v1
	ds_read_b128 v[184:187], v1 offset:1024
	ds_read_b128 v[188:191], v1 offset:2048
	ds_read_b128 v[192:195], v1 offset:3072
	global_load_lds_dwordx4 v[210:211], off
	v_lshl_add_u64 v[210:211], v[212:213], 0, s[86:87]
	s_add_i32 m0, s11, 0x2000
	s_nop 0
	global_load_lds_dwordx4 v[210:211], off
	s_waitcnt vmcnt(10)
	s_barrier
	s_waitcnt lgkmcnt(0)
	s_waitcnt lgkmcnt(0)
	v_mfma_f32_16x16x32_f16 v[116:119], v[180:183], v[148:151], v[116:119]
	v_mfma_f32_16x16x32_f16 v[120:123], v[188:191], v[148:151], v[120:123]
	v_mfma_f32_16x16x32_f16 v[100:103], v[180:183], v[156:159], v[100:103]
	v_mfma_f32_16x16x32_f16 v[104:107], v[188:191], v[156:159], v[104:107]
	v_mfma_f32_16x16x32_f16 v[84:87], v[180:183], v[164:167], v[84:87]
	v_mfma_f32_16x16x32_f16 v[88:91], v[188:191], v[164:167], v[88:91]
	v_mfma_f32_16x16x32_f16 v[68:71], v[180:183], v[172:175], v[68:71]
	v_mfma_f32_16x16x32_f16 v[72:75], v[188:191], v[172:175], v[72:75]
	v_mfma_f32_16x16x32_f16 v[116:119], v[184:187], v[152:155], v[116:119]
	v_mfma_f32_16x16x32_f16 v[120:123], v[192:195], v[152:155], v[120:123]
	v_mfma_f32_16x16x32_f16 v[100:103], v[184:187], v[160:163], v[100:103]
	v_mfma_f32_16x16x32_f16 v[104:107], v[192:195], v[160:163], v[104:107]
	v_mfma_f32_16x16x32_f16 v[84:87], v[184:187], v[168:171], v[84:87]
	v_mfma_f32_16x16x32_f16 v[88:91], v[192:195], v[168:171], v[88:91]
	v_mfma_f32_16x16x32_f16 v[68:71], v[184:187], v[176:179], v[68:71]
	v_mfma_f32_16x16x32_f16 v[72:75], v[192:195], v[176:179], v[72:75]
	s_mov_b32 m0, s77
	v_lshl_add_u64 v[210:211], v[214:215], 0, s[86:87]
	s_barrier
	ds_read_b128 v[148:151], v240 offset:49152
	ds_read_b128 v[152:155], v240 offset:50176
	ds_read_b128 v[156:159], v240 offset:51200
	ds_read_b128 v[160:163], v240 offset:52224
	ds_read_b128 v[164:167], v240 offset:53248
	ds_read_b128 v[168:171], v240 offset:54272
	ds_read_b128 v[172:175], v240 offset:55296
	ds_read_b128 v[176:179], v240 offset:56320
	global_load_lds_dwordx4 v[210:211], off
	v_lshl_add_u64 v[210:211], v[216:217], 0, s[86:87]
	s_mov_b32 m0, s64
	s_nop 0
	global_load_lds_dwordx4 v[210:211], off
	s_barrier
	s_waitcnt lgkmcnt(0)
	s_waitcnt lgkmcnt(0)
	v_mfma_f32_16x16x32_f16 v[60:63], v[132:135], v[148:151], v[60:63]
	v_mfma_f32_16x16x32_f16 v[64:67], v[140:143], v[148:151], v[64:67]
	v_mfma_f32_16x16x32_f16 v[44:47], v[132:135], v[156:159], v[44:47]
	v_mfma_f32_16x16x32_f16 v[48:51], v[140:143], v[156:159], v[48:51]
	v_mfma_f32_16x16x32_f16 v[28:31], v[132:135], v[164:167], v[28:31]
	v_mfma_f32_16x16x32_f16 v[32:35], v[140:143], v[164:167], v[32:35]
	v_mfma_f32_16x16x32_f16 v[12:15], v[132:135], v[172:175], v[12:15]
	v_mfma_f32_16x16x32_f16 v[16:19], v[140:143], v[172:175], v[16:19]
	v_mfma_f32_16x16x32_f16 v[60:63], v[136:139], v[152:155], v[60:63]
	v_mfma_f32_16x16x32_f16 v[64:67], v[144:147], v[152:155], v[64:67]
	v_mfma_f32_16x16x32_f16 v[44:47], v[136:139], v[160:163], v[44:47]
	v_mfma_f32_16x16x32_f16 v[48:51], v[144:147], v[160:163], v[48:51]
	v_mfma_f32_16x16x32_f16 v[28:31], v[136:139], v[168:171], v[28:31]
	v_mfma_f32_16x16x32_f16 v[32:35], v[144:147], v[168:171], v[32:35]
	v_mfma_f32_16x16x32_f16 v[12:15], v[136:139], v[176:179], v[12:15]
	v_mfma_f32_16x16x32_f16 v[16:19], v[144:147], v[176:179], v[16:19]
	s_barrier
	s_add_i32 s10, s10, s72
	v_lshl_add_u64 v[132:133], v[218:219], 0, s[86:87]
	s_mov_b32 m0, s10
	s_nop 0
	global_load_lds_dwordx4 v[132:133], off
	v_lshl_add_u64 v[132:133], v[220:221], 0, s[86:87]
	s_add_i32 m0, s10, 0x2000
	s_nop 0
	global_load_lds_dwordx4 v[132:133], off
	s_waitcnt vmcnt(10)
	s_barrier
	v_mfma_f32_16x16x32_f16 v[52:55], v[180:183], v[148:151], v[52:55]
	v_mfma_f32_16x16x32_f16 v[56:59], v[188:191], v[148:151], v[56:59]
	v_mfma_f32_16x16x32_f16 v[36:39], v[180:183], v[156:159], v[36:39]
	v_mfma_f32_16x16x32_f16 v[40:43], v[188:191], v[156:159], v[40:43]
	v_mfma_f32_16x16x32_f16 v[20:23], v[180:183], v[164:167], v[20:23]
	v_mfma_f32_16x16x32_f16 v[24:27], v[188:191], v[164:167], v[24:27]
	v_mfma_f32_16x16x32_f16 v[8:11], v[180:183], v[172:175], v[8:11]
	v_mfma_f32_16x16x32_f16 v[4:7], v[188:191], v[172:175], v[4:7]
	v_mfma_f32_16x16x32_f16 v[52:55], v[184:187], v[152:155], v[52:55]
	v_mfma_f32_16x16x32_f16 v[56:59], v[192:195], v[152:155], v[56:59]
	v_mfma_f32_16x16x32_f16 v[36:39], v[184:187], v[160:163], v[36:39]
	v_mfma_f32_16x16x32_f16 v[40:43], v[192:195], v[160:163], v[40:43]
	v_mfma_f32_16x16x32_f16 v[20:23], v[184:187], v[168:171], v[20:23]
	v_mfma_f32_16x16x32_f16 v[24:27], v[192:195], v[168:171], v[24:27]
	v_mfma_f32_16x16x32_f16 v[8:11], v[184:187], v[176:179], v[8:11]
	v_mfma_f32_16x16x32_f16 v[4:7], v[192:195], v[176:179], v[4:7]
	s_add_u32 s4, s4, 0x100
	s_addc_u32 s5, s5, 0
	s_add_u32 s1, s1, 0x100
	s_addc_u32 vcc_lo, vcc_lo, 0
	s_cmp_ge_i32 vcc_hi, s67
	s_mov_b32 s10, vcc_hi
	s_barrier
	s_cbranch_scc0 .LBB0_376

.LBB0_455:
	s_setprio 0
	s_waitcnt vmcnt(0)
	s_cmpk_gt_u32 s6, 0xff
	v_readlane_b32 s2, v254, 33
	v_readlane_b32 s3, v254, 34
	s_cbranch_scc1 .LBB0_298
	s_barrier
	s_branch .LBB0_298
